# MLA attention LDS rows restrided (K 400->416 B, V^T 144->160 B) so the 16x16x32 fragment ds_read_b128 are bank-conflict-free
# speedup vs baseline: 1.0226x; 1.0170x over previous
.LBB0_274:
	s_or_b64 exec, exec, s[4:5]
	s_cmpk_lt_i32 s2, 0x400
	s_cselect_b64 s[0:1], -1, 0
	v_writelane_b32 v246, s0, 40
	s_cmpk_lt_i32 s2, 0x100
	s_mul_i32 s31, s31, s30
	v_writelane_b32 v246, s1, 41
	s_cselect_b64 s[0:1], -1, 0
	v_writelane_b32 v246, s0, 42
	s_mul_i32 s31, s31, s3
	s_movk_i32 s78, 0x400
	v_writelane_b32 v246, s1, 43
	s_movk_i32 s28, 0x600
	v_readlane_b32 s4, v246, 0
	v_readlane_b32 s16, v246, 12
	v_readlane_b32 s17, v246, 13
	s_cmp_lg_u64 s[16:17], 0
	s_cselect_b64 s[34:35], -1, 0
	s_cmpk_lt_i32 s2, 0xc0
	s_cselect_b64 s[0:1], -1, 0
	s_lshl_b32 s71, s30, 3
	v_readlane_b32 s5, v246, 1
	v_readlane_b32 s6, v246, 2
	v_readlane_b32 s7, v246, 3
	v_readlane_b32 s8, v246, 4
	v_readlane_b32 s9, v246, 5
	v_readlane_b32 s10, v246, 6
	v_readlane_b32 s11, v246, 7
	v_readlane_b32 s12, v246, 8
	v_readlane_b32 s13, v246, 9
	v_readlane_b32 s14, v246, 10
	v_readlane_b32 s15, v246, 11
	v_readlane_b32 s18, v246, 14
	v_readlane_b32 s19, v246, 15
	v_writelane_b32 v246, s0, 44
	s_cmpk_lt_i32 s2, 0x380
	s_mov_b32 s29, 0x2aaaaaab
	v_writelane_b32 v246, s1, 45
	s_cselect_b64 s[0:1], -1, 0
	s_abs_i32 s4, s30
	s_waitcnt lgkmcnt(0)
	v_cvt_f32_u32_e32 v0, s4
	s_sub_i32 s5, 0, s4
	s_add_i32 s3, s30, 0x1ff
	v_writelane_b32 v246, s0, 46
	v_rcp_iflag_f32_e32 v0, v0
	s_mov_b32 s46, 0x3ffff0
	v_writelane_b32 v246, s1, 47
	s_movk_i32 s0, 0x180
	v_mul_f32_e32 v0, 0x4f7ffffe, v0
	v_cvt_u32_f32_e32 v0, v0
	v_mov_b32_e32 v1, 0
	s_mov_b32 s36, 0x10000
	s_movk_i32 s38, 0xc000
	v_readfirstlane_b32 s6, v0
	s_mul_i32 s5, s5, s6
	s_mul_hi_u32 s5, s6, s5
	s_add_i32 s6, s6, s5
	s_mul_hi_u32 s5, s6, 0x180
	s_mul_i32 s5, s5, s4
	s_sub_i32 s5, 0x180, s5
	s_sub_i32 s7, s5, s4
	s_cmp_ge_u32 s5, s4
	s_cselect_b32 s5, s7, s5
	s_sub_i32 s7, s5, s4
	s_cmp_ge_u32 s5, s4
	s_cselect_b32 s5, s7, s5
	s_sub_i32 s1, 0x180, s5
	s_cmp_lt_i32 s2, s1
	s_cselect_b64 s[8:9], -1, 0
	s_lshl_b32 s68, s5, 1
	v_writelane_b32 v246, s8, 48
	s_cmp_lt_i32 s2, s68
	s_mov_b32 s41, 0xc2fc0000
	v_writelane_b32 v246, s9, 49
	s_cselect_b64 s[8:9], -1, 0
	s_sub_i32 s7, 0xfffffe01, s30
	s_xor_b32 s5, s3, s30
	s_max_i32 s3, s3, s7
	v_writelane_b32 v246, s8, 50
	s_mul_hi_u32 s7, s3, s6
	s_ashr_i32 s5, s5, 31
	v_writelane_b32 v246, s9, 51
	s_mul_i32 s8, s7, s4
	s_sub_i32 s3, s3, s8
	s_add_i32 s8, s7, 1
	s_sub_i32 s9, s3, s4
	s_cmp_ge_u32 s3, s4
	s_cselect_b32 s7, s8, s7
	s_cselect_b32 s3, s9, s3
	s_add_i32 s8, s7, 1
	s_cmp_ge_u32 s3, s4
	s_cselect_b32 s3, s8, s7
	s_xor_b32 s3, s3, s5
	s_sub_i32 s69, s3, s5
	s_mul_hi_u32 s3, s6, 0x580
	s_cmp_gt_i32 s69, 0
	s_mul_i32 s3, s3, s4
	s_cselect_b64 s[8:9], -1, 0
	s_sub_i32 s3, 0x580, s3
	s_sub_i32 s5, s3, s4
	s_cmp_ge_u32 s3, s4
	s_cselect_b32 s3, s5, s3
	s_sub_i32 s5, s3, s4
	s_cmp_ge_u32 s3, s4
	s_cselect_b32 s3, s5, s3
	s_sub_i32 s33, 0x580, s3
	v_writelane_b32 v246, s8, 52
	s_cmp_lt_i32 s2, s33
	s_cselect_b64 s[4:5], -1, 0
	v_writelane_b32 v246, s9, 53
	s_lshl_b32 s47, s3, 1
	v_writelane_b32 v246, s4, 54
	s_cmp_lt_i32 s2, s47
	s_mov_b32 s3, 0x18000
	v_writelane_b32 v246, s5, 55
	s_cselect_b64 s[4:5], -1, 0
	v_writelane_b32 v246, s4, 56
	s_add_i32 s39, s3, 0x400
	s_movk_i32 s3, 0x4800
	v_writelane_b32 v246, s5, 57
	s_addk_i32 s3, 0x400
	v_writelane_b32 v246, s3, 58
	s_mov_b32 s3, 0xd000
	s_addk_i32 s3, 0x400
	s_movk_i32 s37, 0x80
	v_mov_b32_e32 v163, 0x3000
	v_mov_b32_e32 v165, 1
	s_movk_i32 s49, 0x90
	s_mov_b32 s42, 0x800000
	s_movk_i32 s43, 0x3fff
	s_movk_i32 s44, 0x300
	s_movk_i32 s45, 0xc00
	s_movk_i32 s48, 0x1a0
	v_writelane_b32 v246, s3, 59
	v_mov_b32_e32 v178, 0x3727c5ac
	s_movk_i32 s79, 0x1600
	v_mov_b32_e32 v179, 0x400
	v_mov_b32_e32 v180, 0x3e38aa3b
	v_mov_b32_e32 v181, 0x42800000
	v_not_b32_e32 v182, 63
	v_mov_b32_e32 v183, 0x1200
	v_mov_b32_e32 v184, 0xff800000
	v_mov_b32_e32 v164, 0x358637bd
	v_bfrev_b32_e32 v185, 0.5
	s_mov_b32 s3, 0
	s_mov_b32 s55, 0
	s_mov_b32 s70, 0x3fd744fd
	s_barrier
	s_branch .LBB0_278

.LBB0_761:
	v_add_u32_e32 v238, v209, v200
	ds_read_b128 v[218:221], v238
	ds_read_b128 v[222:225], v238 offset:2560
	ds_read_b128 v[226:229], v238 offset:5120
	ds_read_b128 v[230:233], v238 offset:7680
	s_waitcnt lgkmcnt(3)
	v_mfma_f32_16x16x32_bf16 v[2:5], v[218:221], v[150:153], v[2:5]
	v_mfma_f32_16x16x32_bf16 v[6:9], v[218:221], v[154:157], v[6:9]
	ds_read_b128 v[234:237], v238 offset:10240
	s_waitcnt lgkmcnt(3)
	v_mfma_f32_16x16x32_bf16 v[10:13], v[222:225], v[150:153], v[10:13]
	v_mfma_f32_16x16x32_bf16 v[14:17], v[222:225], v[154:157], v[14:17]
	ds_read_b128 v[218:221], v238 offset:12800
	s_waitcnt lgkmcnt(3)
	v_mfma_f32_16x16x32_bf16 v[18:21], v[226:229], v[150:153], v[18:21]
	v_mfma_f32_16x16x32_bf16 v[22:25], v[226:229], v[154:157], v[22:25]
	ds_read_b128 v[222:225], v238 offset:15360
	s_waitcnt lgkmcnt(3)
	v_mfma_f32_16x16x32_bf16 v[26:29], v[230:233], v[150:153], v[26:29]
	v_mfma_f32_16x16x32_bf16 v[30:33], v[230:233], v[154:157], v[30:33]
	ds_read_b128 v[226:229], v238 offset:17920
	s_waitcnt lgkmcnt(3)
	v_mfma_f32_16x16x32_bf16 v[34:37], v[234:237], v[150:153], v[34:37]
	v_mfma_f32_16x16x32_bf16 v[38:41], v[234:237], v[154:157], v[38:41]
	s_waitcnt lgkmcnt(2)
	v_mfma_f32_16x16x32_bf16 v[42:45], v[218:221], v[150:153], v[42:45]
	v_mfma_f32_16x16x32_bf16 v[46:49], v[218:221], v[154:157], v[46:49]
	s_waitcnt lgkmcnt(1)
	v_mfma_f32_16x16x32_bf16 v[50:53], v[222:225], v[150:153], v[50:53]
	v_mfma_f32_16x16x32_bf16 v[54:57], v[222:225], v[154:157], v[54:57]
	s_waitcnt lgkmcnt(0)
	v_mfma_f32_16x16x32_bf16 v[58:61], v[226:229], v[150:153], v[58:61]
	v_mfma_f32_16x16x32_bf16 v[62:65], v[226:229], v[154:157], v[62:65]
	ds_bpermute_b32 v245, v208, v199
	ds_bpermute_b32 v247, v208, v203
	s_waitcnt lgkmcnt(0)
	v_add_f32_e32 v199, v199, v245
	v_add_f32_e32 v203, v203, v247
	ds_bpermute_b32 v245, v198, v199
	ds_bpermute_b32 v247, v198, v203
	s_waitcnt lgkmcnt(0)
	v_add_f32_e32 v199, v199, v245
	v_add_f32_e32 v203, v203, v247
	s_barrier
	v_div_scale_f32 v66, s[6:7], v199, v199, 1.0
	v_rcp_f32_e32 v67, v66
	s_nop 0
	v_fma_f32 v68, -v66, v67, 1.0
	v_fmac_f32_e32 v67, v68, v67
	v_div_scale_f32 v68, vcc, 1.0, v199, 1.0
	v_mul_f32_e32 v69, v68, v67
	v_fma_f32 v70, -v66, v69, v68
	v_fmac_f32_e32 v69, v70, v67
	v_fma_f32 v66, -v66, v69, v68
	v_div_fmas_f32 v66, v66, v67, v69
	v_div_fixup_f32 v66, v66, v199, 1.0
	v_div_scale_f32 v74, s[6:7], v203, v203, 1.0
	v_rcp_f32_e32 v75, v74
	s_nop 0
	v_fma_f32 v76, -v74, v75, 1.0
	v_fmac_f32_e32 v75, v76, v75
	v_div_scale_f32 v76, vcc, 1.0, v203, 1.0
	v_mul_f32_e32 v77, v76, v75
	v_fma_f32 v78, -v74, v77, v76
	v_fmac_f32_e32 v77, v78, v75
	v_fma_f32 v74, -v74, v77, v76
	v_div_fmas_f32 v74, v74, v75, v77
	v_div_fixup_f32 v74, v74, v203, 1.0
	s_lshl_b32 s4, s86, 8
	s_add_u32 s4, s75, s4
	s_addc_u32 s5, s76, 0
	v_ashrrev_i32_e32 v159, 31, v158
	v_lshlrev_b64 v[238:239], 11, v[158:159]
	v_lshl_add_u64 v[238:239], s[4:5], 0, v[238:239]
	v_bfe_u32 v0, v162, 4, 2
	v_lshlrev_b32_e32 v0, 3, v0
	v_lshl_add_u64 v[238:239], v[238:239], 0, v[0:1]
	v_add_co_u32_e32 v244, vcc, 0x8000, v238
	s_nop 1
	v_addc_co_u32_e32 v245, vcc, 0, v239, vcc
	v_mul_f32_e32 v2, v2, v66
	v_mul_f32_e32 v3, v3, v66
	v_mul_f32_e32 v4, v4, v66
	v_mul_f32_e32 v5, v5, v66
	v_cvt_pk_bf16_f32 v240, v2, v3
	v_cvt_pk_bf16_f32 v241, v4, v5
	global_store_dwordx2 v[238:239], v[240:241], off
	v_mul_f32_e32 v6, v6, v74
	v_mul_f32_e32 v7, v7, v74
	v_mul_f32_e32 v8, v8, v74
	v_mul_f32_e32 v9, v9, v74
	v_cvt_pk_bf16_f32 v242, v6, v7
	v_cvt_pk_bf16_f32 v243, v8, v9
	global_store_dwordx2 v[244:245], v[242:243], off
	v_mul_f32_e32 v10, v10, v66
	v_mul_f32_e32 v11, v11, v66
	v_mul_f32_e32 v12, v12, v66
	v_mul_f32_e32 v13, v13, v66
	v_cvt_pk_bf16_f32 v240, v10, v11
	v_cvt_pk_bf16_f32 v241, v12, v13
	global_store_dwordx2 v[238:239], v[240:241], off offset:32
	v_mul_f32_e32 v14, v14, v74
	v_mul_f32_e32 v15, v15, v74
	v_mul_f32_e32 v16, v16, v74
	v_mul_f32_e32 v17, v17, v74
	v_cvt_pk_bf16_f32 v242, v14, v15
	v_cvt_pk_bf16_f32 v243, v16, v17
	global_store_dwordx2 v[244:245], v[242:243], off offset:32
	v_mul_f32_e32 v18, v18, v66
	v_mul_f32_e32 v19, v19, v66
	v_mul_f32_e32 v20, v20, v66
	v_mul_f32_e32 v21, v21, v66
	v_cvt_pk_bf16_f32 v240, v18, v19
	v_cvt_pk_bf16_f32 v241, v20, v21
	global_store_dwordx2 v[238:239], v[240:241], off offset:64
	v_mul_f32_e32 v22, v22, v74
	v_mul_f32_e32 v23, v23, v74
	v_mul_f32_e32 v24, v24, v74
	v_mul_f32_e32 v25, v25, v74
	v_cvt_pk_bf16_f32 v242, v22, v23
	v_cvt_pk_bf16_f32 v243, v24, v25
	global_store_dwordx2 v[244:245], v[242:243], off offset:64
	v_mul_f32_e32 v26, v26, v66
	v_mul_f32_e32 v27, v27, v66
	v_mul_f32_e32 v28, v28, v66
	v_mul_f32_e32 v29, v29, v66
	v_cvt_pk_bf16_f32 v240, v26, v27
	v_cvt_pk_bf16_f32 v241, v28, v29
	global_store_dwordx2 v[238:239], v[240:241], off offset:96
	v_mul_f32_e32 v30, v30, v74
	v_mul_f32_e32 v31, v31, v74
	v_mul_f32_e32 v32, v32, v74
	v_mul_f32_e32 v33, v33, v74
	v_cvt_pk_bf16_f32 v242, v30, v31
	v_cvt_pk_bf16_f32 v243, v32, v33
	global_store_dwordx2 v[244:245], v[242:243], off offset:96
	v_mul_f32_e32 v34, v34, v66
	v_mul_f32_e32 v35, v35, v66
	v_mul_f32_e32 v36, v36, v66
	v_mul_f32_e32 v37, v37, v66
	v_cvt_pk_bf16_f32 v240, v34, v35
	v_cvt_pk_bf16_f32 v241, v36, v37
	global_store_dwordx2 v[238:239], v[240:241], off offset:128
	v_mul_f32_e32 v38, v38, v74
	v_mul_f32_e32 v39, v39, v74
	v_mul_f32_e32 v40, v40, v74
	v_mul_f32_e32 v41, v41, v74
	v_cvt_pk_bf16_f32 v242, v38, v39
	v_cvt_pk_bf16_f32 v243, v40, v41
	global_store_dwordx2 v[244:245], v[242:243], off offset:128
	v_mul_f32_e32 v42, v42, v66
	v_mul_f32_e32 v43, v43, v66
	v_mul_f32_e32 v44, v44, v66
	v_mul_f32_e32 v45, v45, v66
	v_cvt_pk_bf16_f32 v240, v42, v43
	v_cvt_pk_bf16_f32 v241, v44, v45
	global_store_dwordx2 v[238:239], v[240:241], off offset:160
	v_mul_f32_e32 v46, v46, v74
	v_mul_f32_e32 v47, v47, v74
	v_mul_f32_e32 v48, v48, v74
	v_mul_f32_e32 v49, v49, v74
	v_cvt_pk_bf16_f32 v242, v46, v47
	v_cvt_pk_bf16_f32 v243, v48, v49
	global_store_dwordx2 v[244:245], v[242:243], off offset:160
	v_mul_f32_e32 v50, v50, v66
	v_mul_f32_e32 v51, v51, v66
	v_mul_f32_e32 v52, v52, v66
	v_mul_f32_e32 v53, v53, v66
	v_cvt_pk_bf16_f32 v240, v50, v51
	v_cvt_pk_bf16_f32 v241, v52, v53
	global_store_dwordx2 v[238:239], v[240:241], off offset:192
	v_mul_f32_e32 v54, v54, v74
	v_mul_f32_e32 v55, v55, v74
	v_mul_f32_e32 v56, v56, v74
	v_mul_f32_e32 v57, v57, v74
	v_cvt_pk_bf16_f32 v242, v54, v55
	v_cvt_pk_bf16_f32 v243, v56, v57
	global_store_dwordx2 v[244:245], v[242:243], off offset:192
	v_mul_f32_e32 v58, v58, v66
	v_mul_f32_e32 v59, v59, v66
	v_mul_f32_e32 v60, v60, v66
	v_mul_f32_e32 v61, v61, v66
	v_cvt_pk_bf16_f32 v240, v58, v59
	v_cvt_pk_bf16_f32 v241, v60, v61
	global_store_dwordx2 v[238:239], v[240:241], off offset:224
	v_mul_f32_e32 v62, v62, v74
	v_mul_f32_e32 v63, v63, v74
	v_mul_f32_e32 v64, v64, v74
	v_mul_f32_e32 v65, v65, v74
	v_cvt_pk_bf16_f32 v242, v62, v63
	v_cvt_pk_bf16_f32 v243, v64, v65
	global_store_dwordx2 v[244:245], v[242:243], off offset:224

.LBB0_763:
	s_and_b32 s4, s77, 1
	s_add_i32 s5, s77, s4
	s_sub_i32 s4, 0, s4
	s_xor_b32 s4, s2, s4
	s_mul_i32 s5, s5, s30
	s_add_i32 s4, s5, s4
	s_cmpk_gt_i32 s4, 0x1ff
	s_cbranch_scc1 .LBB0_762
	s_and_b32 s86, s4, 7
	s_mul_i32 s5, s86, 0x180
	s_add_u32 s10, s40, s5
	s_addc_u32 s11, s60, 0
	s_mul_i32 s5, s86, 0x600000
	s_add_u32 s6, s61, s5
	s_addc_u32 s7, s72, 0
	s_lshl_b32 s5, s86, 22
	s_add_u32 s8, s73, s5
	v_mov_b32_e32 v22, v162
	s_addc_u32 s9, s74, 0
	s_lshl_b32 s4, s4, 5
	s_and_b32 s54, s4, 0xffffff00
	v_ashrrev_i32_e32 v0, 1, v22
	v_and_b32_e32 v0, 0xffffffe0, v0
	v_subrev_u32_e32 v38, s54, v0
	v_and_b32_e32 v36, 31, v22
	v_add_u32_e32 v186, 0x3f00, v38
	v_bfe_u32 v37, v22, 5, 1
	v_or_b32_e32 v158, v186, v36
	v_and_b32_e32 v4, 15, v22
	v_bfe_u32 v5, v22, 4, 2
	v_add_u32_e32 v158, v186, v4
	v_lshlrev_b32_e32 v0, 4, v5
	v_mov_b64_e32 v[2:3], s[10:11]
	v_mad_i64_i32 v[2:3], s[4:5], v158, s45, v[2:3]
	v_lshl_add_u64 v[2:3], v[2:3], 0, v[0:1]
	v_add_co_u32_e32 v4, vcc, 0xc000, v2
	s_nop 1
	v_addc_co_u32_e32 v5, vcc, 0, v3, vcc
	global_load_dwordx4 v[82:85], v[2:3], off
	global_load_dwordx4 v[86:89], v[2:3], off offset:64
	global_load_dwordx4 v[90:93], v[2:3], off offset:128
	global_load_dwordx4 v[94:97], v[2:3], off offset:192
	global_load_dwordx4 v[98:101], v[2:3], off offset:256
	global_load_dwordx4 v[102:105], v[2:3], off offset:320
	global_load_dwordx4 v[106:109], v[4:5], off
	global_load_dwordx4 v[110:113], v[4:5], off offset:64
	global_load_dwordx4 v[114:117], v[4:5], off offset:128
	global_load_dwordx4 v[118:121], v[4:5], off offset:192
	global_load_dwordx4 v[122:125], v[4:5], off offset:256
	global_load_dwordx4 v[126:129], v[4:5], off offset:320
	v_add_u32_e32 v24, 0x200, v22
	v_ashrrev_i32_e32 v25, 31, v24
	v_ashrrev_i32_e32 v23, 31, v22
	v_lshrrev_b32_e32 v18, 29, v25
	v_lshrrev_b32_e32 v12, 29, v23
	v_add_u32_e32 v20, v24, v18
	v_add_u32_e32 v14, v22, v12
	v_ashrrev_i32_e32 v32, 3, v20
	v_and_b32_e32 v20, -8, v20
	v_lshlrev_b64 v[166:167], 4, v[24:25]
	v_add_u32_e32 v26, 0x400, v22
	v_ashrrev_i32_e32 v28, 3, v14
	v_and_b32_e32 v14, -8, v14
	v_ashrrev_i32_e32 v33, 31, v32
	v_sub_u32_e32 v25, v24, v20
	v_lshlrev_b64 v[160:161], 4, v[22:23]
	v_ashrrev_i32_e32 v27, 31, v26
	v_ashrrev_i32_e32 v29, 31, v28
	v_sub_u32_e32 v23, v22, v14
	v_lshlrev_b64 v[174:175], 15, v[32:33]
	v_lshlrev_b32_e32 v176, 3, v25
	v_lshlrev_b64 v[168:169], 4, v[26:27]
	v_lshlrev_b64 v[170:171], 15, v[28:29]
	v_lshlrev_b32_e32 v172, 3, v23
	v_lshl_add_u64 v[18:19], s[8:9], 0, v[174:175]
	v_ashrrev_i32_e32 v177, 31, v176
	v_lshl_add_u64 v[2:3], s[6:7], 0, v[160:161]
	v_lshl_add_u64 v[6:7], s[6:7], 0, v[166:167]
	v_lshl_add_u64 v[10:11], s[6:7], 0, v[168:169]
	v_lshl_add_u64 v[12:13], s[8:9], 0, v[170:171]
	v_ashrrev_i32_e32 v173, 31, v172
	v_lshl_add_u64 v[34:35], v[176:177], 1, v[18:19]
	global_load_dwordx4 v[2:5], v[2:3], off
	s_nop 0
	global_load_dwordx4 v[6:9], v[6:7], off
	v_lshl_add_u64 v[30:31], v[172:173], 1, v[12:13]
	global_load_dwordx4 v[10:13], v[10:11], off
	s_nop 0
	global_load_dwordx4 v[14:17], v[30:31], off
	global_load_dwordx4 v[18:21], v[34:35], off
	s_sub_i32 s4, 0x4000, s54
	v_and_b32_e32 v27, 63, v22
	v_ashrrev_i32_e32 v159, 31, v158
	v_mul_hi_i32 v29, v22, s29
	v_lshrrev_b32_e32 v33, 31, v29
	v_ashrrev_i32_e32 v29, 2, v29
	v_add_u32_e32 v29, v29, v33
	v_mul_lo_u32 v187, v29, s48
	v_mul_lo_u32 v29, v29, 24
	v_sub_u32_e32 v22, v22, v29
	v_lshlrev_b32_e32 v188, 4, v22
	v_add3_u32 v22, s78, v187, v188
	s_waitcnt vmcnt(4)
	ds_write_b128 v22, v[2:5]
	v_mul_hi_i32 v2, v24, s29
	v_lshrrev_b32_e32 v3, 31, v2
	v_ashrrev_i32_e32 v2, 2, v2
	v_add_u32_e32 v2, v2, v3
	v_mul_lo_u32 v189, v2, s48
	v_mul_lo_u32 v2, v2, 24
	v_sub_u32_e32 v2, v24, v2
	v_lshlrev_b32_e32 v190, 4, v2
	v_add3_u32 v2, s78, v189, v190
	s_waitcnt vmcnt(3)
	ds_write_b128 v2, v[6:9]
	v_mul_hi_i32 v2, v26, s29
	v_lshrrev_b32_e32 v3, 31, v2
	v_ashrrev_i32_e32 v2, 2, v2
	v_add_u32_e32 v2, v2, v3
	v_mul_lo_u32 v191, v2, s48
	v_mul_lo_u32 v2, v2, 24
	v_sub_u32_e32 v2, v26, v2
	v_lshlrev_b32_e32 v192, 4, v2
	s_movk_i32 s5, 0xa0
	v_add3_u32 v2, s78, v191, v192
	v_mul_lo_u32 v193, v28, s5
	v_lshlrev_b32_e32 v194, 4, v23
	s_waitcnt vmcnt(2)
	ds_write_b128 v2, v[10:13]
	v_add3_u32 v2, s78, v193, v194
	v_mul_lo_u32 v195, v32, s5
	v_lshlrev_b32_e32 v196, 4, v25
	s_add_u32 s10, s6, 0x6000
	s_waitcnt vmcnt(1)
	ds_write_b128 v2, v[14:17] offset:53248
	v_add3_u32 v2, s78, v195, v196
	s_addc_u32 s11, s7, 0
	s_waitcnt vmcnt(0)
	ds_write_b128 v2, v[18:21] offset:53248
	s_movk_i32 s49, 0x90
	s_lshr_b32 s87, s4, 6
	v_mul_u32_u24_e32 v2, 0x190, v36
	v_add3_u32 v202, s78, v2, v0
	v_lshlrev_b32_e32 v2, 2, v27
	v_mov_b32_e32 v50, v1
	v_mov_b32_e32 v51, v1
	v_add_u32_e32 v201, 0x3f3f, v38
	v_add_u32_e32 v203, 0x3f1f, v38
	v_lshlrev_b32_e32 v197, 2, v37
	v_xor_b32_e32 v198, 0x80, v2
	v_mul_u32_u24_e32 v200, 0x90, v36
	v_mov_b32_e32 v52, v1
	v_mov_b32_e32 v53, v1
	v_mov_b32_e32 v54, v1
	v_mov_b32_e32 v55, v1
	v_mov_b32_e32 v56, v1
	v_mov_b32_e32 v57, v1
	v_mov_b32_e32 v58, v1
	v_mov_b32_e32 v59, v1
	v_mov_b32_e32 v60, v1
	v_mov_b32_e32 v61, v1
	v_mov_b32_e32 v62, v1
	v_mov_b32_e32 v63, v1
	v_mov_b32_e32 v64, v1
	v_mov_b32_e32 v65, v1
	v_readlane_b32 s5, v246, 59
	v_mov_b64_e32 v[34:35], v[50:51]
	v_mov_b64_e32 v[18:19], v[50:51]
	v_mov_b64_e32 v[2:3], v[50:51]
	s_mov_b32 s4, 0
	v_mov_b32_e32 v199, 0
	v_mov_b32_e32 v206, 0xf149f2ca
	v_mov_b32_e32 v209, s5
	v_mov_b32_e32 v154, 0
	v_mov_b32_e32 v155, 0
	v_mov_b32_e32 v156, 0
	v_mov_b32_e32 v157, 0
	v_mov_b32_e32 v150, 0
	v_mov_b32_e32 v151, 0
	v_mov_b32_e32 v152, 0
	v_mov_b32_e32 v153, 0
	v_mov_b64_e32 v[36:37], v[52:53]
	v_mov_b64_e32 v[38:39], v[54:55]
	v_mov_b64_e32 v[40:41], v[56:57]
	v_mov_b64_e32 v[42:43], v[58:59]
	v_mov_b64_e32 v[44:45], v[60:61]
	v_mov_b64_e32 v[46:47], v[62:63]
	v_mov_b64_e32 v[48:49], v[64:65]
	v_mov_b64_e32 v[20:21], v[52:53]
	v_mov_b64_e32 v[22:23], v[54:55]
	v_mov_b64_e32 v[24:25], v[56:57]
	v_mov_b64_e32 v[26:27], v[58:59]
	v_mov_b64_e32 v[28:29], v[60:61]
	v_mov_b64_e32 v[30:31], v[62:63]
	v_mov_b64_e32 v[32:33], v[64:65]
	v_mov_b64_e32 v[4:5], v[52:53]
	v_mov_b64_e32 v[6:7], v[54:55]
	v_mov_b64_e32 v[8:9], v[56:57]
	v_mov_b64_e32 v[10:11], v[58:59]
	v_mov_b64_e32 v[12:13], v[60:61]
	v_mov_b64_e32 v[14:15], v[62:63]
	v_mov_b64_e32 v[16:17], v[64:65]
	v_and_b32_e32 v239, 15, v162
	v_bfe_u32 v244, v162, 4, 2
	v_lshrrev_b32_e32 v245, 3, v239
	v_lshl_add_u32 v245, v245, 3, v239
	v_mul_u32_u24_e32 v245, 0x1a0, v245
	v_lshlrev_b32_e32 v205, 4, v244
	v_add3_u32 v202, s78, v245, v205
	v_mul_u32_u24_e32 v245, 0xa0, v239
	v_add_u32_e32 v200, v245, v205
	v_lshrrev_b32_e32 v245, 1, v244
	v_lshlrev_b32_e32 v245, 3, v245
	v_lshl_add_u32 v245, v244, 2, v245
	v_sub_u32_e32 v197, v245, v239
	v_and_b32_e32 v245, 63, v162
	v_xor_b32_e32 v245, 16, v245
	v_lshlrev_b32_e32 v208, 2, v245
	v_mov_b32_e32 v206, 0
	v_mov_b32_e32 v201, 0
	v_mov_b32_e32 v203, 0
	s_mov_b32 s21, 0
	v_mov_b32_e32 v210, 0
	v_mov_b32_e32 v211, 0
	v_mov_b32_e32 v212, 0
	v_mov_b32_e32 v213, 0
	v_mov_b32_e32 v214, 0
	v_mov_b32_e32 v215, 0
	v_mov_b32_e32 v216, 0
	v_mov_b32_e32 v217, 0
	v_readfirstlane_b32 s12, v186
	v_add_u32_e32 v244, 0, v162
	v_mul_u32_u24_e32 v245, 0x9d9, v244
	v_lshrrev_b32_e32 v245, 16, v245
	v_mul_u32_u24_e32 v239, 26, v245
	v_sub_u32_e32 v244, v244, v239
	v_min_u32_e32 v244, 23, v244
	v_mul_u32_u24_e32 v245, 0x180, v245
	v_lshl_add_u32 v130, v244, 4, v245
	v_add_u32_e32 v244, 512, v162
	v_mul_u32_u24_e32 v245, 0x9d9, v244
	v_lshrrev_b32_e32 v245, 16, v245
	v_mul_u32_u24_e32 v239, 26, v245
	v_sub_u32_e32 v244, v244, v239
	v_min_u32_e32 v244, 23, v244
	v_mul_u32_u24_e32 v245, 0x180, v245
	v_lshl_add_u32 v131, v244, 4, v245
	v_add_u32_e32 v244, 1024, v162
	v_mul_u32_u24_e32 v245, 0x9d9, v244
	v_lshrrev_b32_e32 v245, 16, v245
	v_mul_u32_u24_e32 v239, 26, v245
	v_sub_u32_e32 v244, v244, v239
	v_min_u32_e32 v244, 23, v244
	v_mul_u32_u24_e32 v245, 0x180, v245
	v_lshl_add_u32 v132, v244, 4, v245
	v_add_u32_e32 v244, 1536, v162
	v_mul_u32_u24_e32 v245, 0x9d9, v244
	v_lshrrev_b32_e32 v245, 16, v245
	v_mul_u32_u24_e32 v239, 26, v245
	v_sub_u32_e32 v244, v244, v239
	v_min_u32_e32 v244, 23, v244
	v_mul_u32_u24_e32 v245, 0x180, v245
	v_lshl_add_u32 v133, v244, 4, v245
	v_add_u32_e32 v244, 0, v162
	v_mul_u32_u24_e32 v245, 0x667, v244
	v_lshrrev_b32_e32 v245, 14, v245
	v_mul_u32_u24_e32 v239, 10, v245
	v_sub_u32_e32 v244, v244, v239
	v_min_u32_e32 v244, 7, v244
	v_lshlrev_b32_e32 v245, 15, v245
	v_lshl_add_u32 v134, v244, 4, v245
	v_add_u32_e32 v244, 512, v162
	v_mul_u32_u24_e32 v245, 0x667, v244
	v_lshrrev_b32_e32 v245, 14, v245
	v_mul_u32_u24_e32 v239, 10, v245
	v_sub_u32_e32 v244, v244, v239
	v_min_u32_e32 v244, 7, v244
	v_lshlrev_b32_e32 v245, 15, v245
	v_lshl_add_u32 v135, v244, 4, v245
	v_add_u32_e32 v244, 1024, v162
	v_mul_u32_u24_e32 v245, 0x667, v244
	v_lshrrev_b32_e32 v245, 14, v245
	v_mul_u32_u24_e32 v239, 10, v245
	v_sub_u32_e32 v244, v244, v239
	v_min_u32_e32 v244, 7, v244
	v_lshlrev_b32_e32 v245, 15, v245
	v_lshl_add_u32 v136, v244, 4, v245
	s_nop 3
	s_lshr_b32 s22, s12, 5
	s_and_b32 s22, s22, 7
	s_lshl_b32 s23, s22, 10
	s_waitcnt lgkmcnt(0)
	s_barrier
	s_and_b32 s5, s4, 1
	s_add_i32 s88, s4, 1
	s_cmp_ge_u32 s88, s87
	s_cbranch_scc1 .LBB0_766
.LBB0_765:
	s_xor_b32 s10, s5, 1
	s_mulk_i32 s10, 0x6800
	s_add_i32 s10, s10, s23
	s_addk_i32 s10, 0x400
	s_mul_i32 s11, s88, 0x6000
	s_add_u32 s16, s6, s11
	s_addc_u32 s17, s7, 0
	s_add_u32 m0, s10, 0x0
	s_nop 0
	global_load_lds_dwordx4 v130, s[16:17]
	s_add_u32 m0, s10, 0x2000
	s_nop 0
	global_load_lds_dwordx4 v131, s[16:17]
	s_add_u32 m0, s10, 0x4000
	s_nop 0
	global_load_lds_dwordx4 v132, s[16:17]
	s_cmp_gt_u32 s22, 1
	s_cbranch_scc1 .Lv3_dma_k3
	s_add_u32 m0, s10, 0x6000
	s_nop 0
	global_load_lds_dwordx4 v133, s[16:17]
.Lv3_dma_k3:
	s_mul_hi_u32 s11, s88, 0xaaaaaaab
	s_lshr_b32 s11, s11, 1
	s_mul_i32 s11, s11, 3
	s_sub_i32 s11, s88, s11
	s_mulk_i32 s11, 0x5000
	s_add_i32 s11, s11, s23
	s_add_i32 s11, s11, 0xd400
	s_lshl_b32 s18, s88, 7
	s_add_u32 s16, s8, s18
	s_addc_u32 s17, s9, 0
	s_add_u32 m0, s11, 0x0
	s_nop 0
	global_load_lds_dwordx4 v134, s[16:17]
	s_add_u32 m0, s11, 0x2000
	s_nop 0
	global_load_lds_dwordx4 v135, s[16:17]
	s_cmp_gt_u32 s22, 3
	s_cbranch_scc1 .Lv3_dma_v2
	s_add_u32 m0, s11, 0x4000
	s_nop 0
	global_load_lds_dwordx4 v136, s[16:17]

.LBB0_768:
	s_mul_hi_u32 s10, s4, 0xaaaaaaab
	s_lshr_b32 s10, s10, 1
	s_mul_i32 s10, s10, 3
	s_sub_i32 s4, s4, s10
	s_mulk_i32 s5, 0x6800
	s_mulk_i32 s4, 0x5000
	s_add_i32 s89, s4, 0x400
	v_add_u32_e32 v204, s5, v202
.Lv3_h0:
	s_mov_b32 s91, s54
	s_add_i32 s13, s12, 63
	s_cmp_le_i32 s91, s13
	s_cbranch_scc0 .Lv3_h0_end
	v_mov_b32_e32 v205, v204
	v_add_u32_e32 v238, v209, v200
	s_add_i32 s4, s89, 0xd000
	ds_read_b128 v[218:221], v205
	ds_read_b128 v[222:225], v205 offset:3328
	ds_read_b128 v[226:229], v205 offset:64
	ds_read_b128 v[230:233], v205 offset:3392
	v_mov_b32_e32 v209, s4
	s_waitcnt lgkmcnt(3)
	v_mfma_f32_16x16x32_bf16 v[66:69], v[218:221], v[82:85], v[210:213]
	v_mfma_f32_16x16x32_bf16 v[70:73], v[218:221], v[106:109], v[214:217]
	ds_read_b128 v[234:237], v205 offset:128
	s_waitcnt lgkmcnt(3)
	v_mfma_f32_16x16x32_bf16 v[74:77], v[222:225], v[82:85], v[210:213]
	v_mfma_f32_16x16x32_bf16 v[78:81], v[222:225], v[106:109], v[214:217]
	ds_read_b128 v[218:221], v205 offset:3456
	s_waitcnt lgkmcnt(3)
	v_mfma_f32_16x16x32_bf16 v[66:69], v[226:229], v[86:89], v[66:69]
	v_mfma_f32_16x16x32_bf16 v[70:73], v[226:229], v[110:113], v[70:73]
	ds_read_b128 v[222:225], v205 offset:192
	s_waitcnt lgkmcnt(3)
	v_mfma_f32_16x16x32_bf16 v[74:77], v[230:233], v[86:89], v[74:77]
	v_mfma_f32_16x16x32_bf16 v[78:81], v[230:233], v[110:113], v[78:81]
	ds_read_b128 v[226:229], v205 offset:3520
	s_waitcnt lgkmcnt(3)
	v_mfma_f32_16x16x32_bf16 v[66:69], v[234:237], v[90:93], v[66:69]
	v_mfma_f32_16x16x32_bf16 v[70:73], v[234:237], v[114:117], v[70:73]
	ds_read_b128 v[230:233], v205 offset:256
	s_waitcnt lgkmcnt(3)
	v_mfma_f32_16x16x32_bf16 v[74:77], v[218:221], v[90:93], v[74:77]
	v_mfma_f32_16x16x32_bf16 v[78:81], v[218:221], v[114:117], v[78:81]
	ds_read_b128 v[234:237], v205 offset:3584
	s_waitcnt lgkmcnt(3)
	v_mfma_f32_16x16x32_bf16 v[66:69], v[222:225], v[94:97], v[66:69]
	v_mfma_f32_16x16x32_bf16 v[70:73], v[222:225], v[118:121], v[70:73]
	ds_read_b128 v[218:221], v205 offset:320
	s_waitcnt lgkmcnt(3)
	v_mfma_f32_16x16x32_bf16 v[74:77], v[226:229], v[94:97], v[74:77]
	v_mfma_f32_16x16x32_bf16 v[78:81], v[226:229], v[118:121], v[78:81]
	ds_read_b128 v[222:225], v205 offset:3648
	s_waitcnt lgkmcnt(3)
	v_mfma_f32_16x16x32_bf16 v[66:69], v[230:233], v[98:101], v[66:69]
	v_mfma_f32_16x16x32_bf16 v[70:73], v[230:233], v[122:125], v[70:73]
	ds_read_b128 v[226:229], v238
	s_waitcnt lgkmcnt(3)
	v_mfma_f32_16x16x32_bf16 v[74:77], v[234:237], v[98:101], v[74:77]
	v_mfma_f32_16x16x32_bf16 v[78:81], v[234:237], v[122:125], v[78:81]
	ds_read_b128 v[230:233], v238 offset:2560
	s_waitcnt lgkmcnt(3)
	v_mfma_f32_16x16x32_bf16 v[66:69], v[218:221], v[102:105], v[66:69]
	v_mfma_f32_16x16x32_bf16 v[70:73], v[218:221], v[126:129], v[70:73]
	ds_read_b128 v[234:237], v238 offset:5120
	s_waitcnt lgkmcnt(3)
	v_mfma_f32_16x16x32_bf16 v[74:77], v[222:225], v[102:105], v[74:77]
	v_mfma_f32_16x16x32_bf16 v[78:81], v[222:225], v[126:129], v[78:81]
	ds_read_b128 v[218:221], v238 offset:7680
	s_waitcnt lgkmcnt(3)
	v_mfma_f32_16x16x32_bf16 v[2:5], v[226:229], v[150:153], v[2:5]
	v_mfma_f32_16x16x32_bf16 v[6:9], v[226:229], v[154:157], v[6:9]
	ds_read_b128 v[222:225], v238 offset:10240
	s_waitcnt lgkmcnt(3)
	v_mfma_f32_16x16x32_bf16 v[10:13], v[230:233], v[150:153], v[10:13]
	v_mfma_f32_16x16x32_bf16 v[14:17], v[230:233], v[154:157], v[14:17]
	ds_read_b128 v[226:229], v238 offset:12800
	s_waitcnt lgkmcnt(3)
	v_mfma_f32_16x16x32_bf16 v[18:21], v[234:237], v[150:153], v[18:21]
	v_mfma_f32_16x16x32_bf16 v[22:25], v[234:237], v[154:157], v[22:25]
	ds_read_b128 v[230:233], v238 offset:15360
	s_waitcnt lgkmcnt(3)
	v_mfma_f32_16x16x32_bf16 v[26:29], v[218:221], v[150:153], v[26:29]
	v_mfma_f32_16x16x32_bf16 v[30:33], v[218:221], v[154:157], v[30:33]
	ds_read_b128 v[234:237], v238 offset:17920
	s_waitcnt lgkmcnt(3)
	v_mfma_f32_16x16x32_bf16 v[34:37], v[222:225], v[150:153], v[34:37]
	v_mfma_f32_16x16x32_bf16 v[38:41], v[222:225], v[154:157], v[38:41]
	s_waitcnt lgkmcnt(2)
	v_mfma_f32_16x16x32_bf16 v[42:45], v[226:229], v[150:153], v[42:45]
	v_mfma_f32_16x16x32_bf16 v[46:49], v[226:229], v[154:157], v[46:49]
	s_waitcnt lgkmcnt(1)
	v_mfma_f32_16x16x32_bf16 v[50:53], v[230:233], v[150:153], v[50:53]
	v_mfma_f32_16x16x32_bf16 v[54:57], v[230:233], v[154:157], v[54:57]
	s_waitcnt lgkmcnt(0)
	v_mfma_f32_16x16x32_bf16 v[58:61], v[234:237], v[150:153], v[58:61]
	v_mfma_f32_16x16x32_bf16 v[62:65], v[234:237], v[154:157], v[62:65]
	s_add_i32 s13, s91, 31
	s_cmp_gt_i32 s13, s12
	s_cbranch_scc1 .Lv3_h0_mask

.Lv3_h0_end:
.Lv3_h1:
	s_add_i32 s91, s54, 32
	s_add_i32 s13, s12, 63
	s_cmp_le_i32 s91, s13
	s_cbranch_scc0 .Lv3_h1_end
	v_add_u32_e32 v205, 0x3400, v204
	v_add_u32_e32 v238, v209, v200
	s_add_i32 s4, s89, 0xd040
	ds_read_b128 v[218:221], v205
	ds_read_b128 v[222:225], v205 offset:3328
	ds_read_b128 v[226:229], v205 offset:64
	ds_read_b128 v[230:233], v205 offset:3392
	v_mov_b32_e32 v209, s4
	s_waitcnt lgkmcnt(3)
	v_mfma_f32_16x16x32_bf16 v[66:69], v[218:221], v[82:85], v[210:213]
	v_mfma_f32_16x16x32_bf16 v[70:73], v[218:221], v[106:109], v[214:217]
	ds_read_b128 v[234:237], v205 offset:128
	s_waitcnt lgkmcnt(3)
	v_mfma_f32_16x16x32_bf16 v[74:77], v[222:225], v[82:85], v[210:213]
	v_mfma_f32_16x16x32_bf16 v[78:81], v[222:225], v[106:109], v[214:217]
	ds_read_b128 v[218:221], v205 offset:3456
	s_waitcnt lgkmcnt(3)
	v_mfma_f32_16x16x32_bf16 v[66:69], v[226:229], v[86:89], v[66:69]
	v_mfma_f32_16x16x32_bf16 v[70:73], v[226:229], v[110:113], v[70:73]
	ds_read_b128 v[222:225], v205 offset:192
	s_waitcnt lgkmcnt(3)
	v_mfma_f32_16x16x32_bf16 v[74:77], v[230:233], v[86:89], v[74:77]
	v_mfma_f32_16x16x32_bf16 v[78:81], v[230:233], v[110:113], v[78:81]
	ds_read_b128 v[226:229], v205 offset:3520
	s_waitcnt lgkmcnt(3)
	v_mfma_f32_16x16x32_bf16 v[66:69], v[234:237], v[90:93], v[66:69]
	v_mfma_f32_16x16x32_bf16 v[70:73], v[234:237], v[114:117], v[70:73]
	ds_read_b128 v[230:233], v205 offset:256
	s_waitcnt lgkmcnt(3)
	v_mfma_f32_16x16x32_bf16 v[74:77], v[218:221], v[90:93], v[74:77]
	v_mfma_f32_16x16x32_bf16 v[78:81], v[218:221], v[114:117], v[78:81]
	ds_read_b128 v[234:237], v205 offset:3584
	s_waitcnt lgkmcnt(3)
	v_mfma_f32_16x16x32_bf16 v[66:69], v[222:225], v[94:97], v[66:69]
	v_mfma_f32_16x16x32_bf16 v[70:73], v[222:225], v[118:121], v[70:73]
	ds_read_b128 v[218:221], v205 offset:320
	s_waitcnt lgkmcnt(3)
	v_mfma_f32_16x16x32_bf16 v[74:77], v[226:229], v[94:97], v[74:77]
	v_mfma_f32_16x16x32_bf16 v[78:81], v[226:229], v[118:121], v[78:81]
	ds_read_b128 v[222:225], v205 offset:3648
	s_waitcnt lgkmcnt(3)
	v_mfma_f32_16x16x32_bf16 v[66:69], v[230:233], v[98:101], v[66:69]
	v_mfma_f32_16x16x32_bf16 v[70:73], v[230:233], v[122:125], v[70:73]
	ds_read_b128 v[226:229], v238
	s_waitcnt lgkmcnt(3)
	v_mfma_f32_16x16x32_bf16 v[74:77], v[234:237], v[98:101], v[74:77]
	v_mfma_f32_16x16x32_bf16 v[78:81], v[234:237], v[122:125], v[78:81]
	ds_read_b128 v[230:233], v238 offset:2560
	s_waitcnt lgkmcnt(3)
	v_mfma_f32_16x16x32_bf16 v[66:69], v[218:221], v[102:105], v[66:69]
	v_mfma_f32_16x16x32_bf16 v[70:73], v[218:221], v[126:129], v[70:73]
	ds_read_b128 v[234:237], v238 offset:5120
	s_waitcnt lgkmcnt(3)
	v_mfma_f32_16x16x32_bf16 v[74:77], v[222:225], v[102:105], v[74:77]
	v_mfma_f32_16x16x32_bf16 v[78:81], v[222:225], v[126:129], v[78:81]
	ds_read_b128 v[218:221], v238 offset:7680
	s_waitcnt lgkmcnt(3)
	v_mfma_f32_16x16x32_bf16 v[2:5], v[226:229], v[150:153], v[2:5]
	v_mfma_f32_16x16x32_bf16 v[6:9], v[226:229], v[154:157], v[6:9]
	ds_read_b128 v[222:225], v238 offset:10240
	s_waitcnt lgkmcnt(3)
	v_mfma_f32_16x16x32_bf16 v[10:13], v[230:233], v[150:153], v[10:13]
	v_mfma_f32_16x16x32_bf16 v[14:17], v[230:233], v[154:157], v[14:17]
	ds_read_b128 v[226:229], v238 offset:12800
	s_waitcnt lgkmcnt(3)
	v_mfma_f32_16x16x32_bf16 v[18:21], v[234:237], v[150:153], v[18:21]
	v_mfma_f32_16x16x32_bf16 v[22:25], v[234:237], v[154:157], v[22:25]
	ds_read_b128 v[230:233], v238 offset:15360
	s_waitcnt lgkmcnt(3)
	v_mfma_f32_16x16x32_bf16 v[26:29], v[218:221], v[150:153], v[26:29]
	v_mfma_f32_16x16x32_bf16 v[30:33], v[218:221], v[154:157], v[30:33]
	ds_read_b128 v[234:237], v238 offset:17920
	s_waitcnt lgkmcnt(3)
	v_mfma_f32_16x16x32_bf16 v[34:37], v[222:225], v[150:153], v[34:37]
	v_mfma_f32_16x16x32_bf16 v[38:41], v[222:225], v[154:157], v[38:41]
	s_waitcnt lgkmcnt(2)
	v_mfma_f32_16x16x32_bf16 v[42:45], v[226:229], v[150:153], v[42:45]
	v_mfma_f32_16x16x32_bf16 v[46:49], v[226:229], v[154:157], v[46:49]
	s_waitcnt lgkmcnt(1)
	v_mfma_f32_16x16x32_bf16 v[50:53], v[230:233], v[150:153], v[50:53]
	v_mfma_f32_16x16x32_bf16 v[54:57], v[230:233], v[154:157], v[54:57]
	s_waitcnt lgkmcnt(0)
	v_mfma_f32_16x16x32_bf16 v[58:61], v[234:237], v[150:153], v[58:61]
	v_mfma_f32_16x16x32_bf16 v[62:65], v[234:237], v[154:157], v[62:65]
	s_add_i32 s13, s91, 31
	s_cmp_gt_i32 s13, s12
	s_cbranch_scc1 .Lv3_h1_mask
